# P9 main-path epilogue: residual loads batched (7 groups in flight), counted vmcnt instead of per-load vmcnt(0) ladder
# speedup vs baseline: 1.0083x; 1.0083x over previous
; __device__ __forceinline__ unsigned cvt_pk_bf16(float lo, float hi) { unsigned r; asm volatile("v_cvt_pk_bf16_f32 %0, %1, %2" : "=v"(r) : "v"(lo), "v"(hi)); return r; }
;     __device__ __forceinline__ void operator()(const f32x4 (&acc)[2][2][4][2], const pg8::Unit& u, int wr, int wc, int fr, int fq) const {
;     ...
;             for (int m = 0; m < 4; ++m) { const int row = row0 + ai * 128 + m * 16;
;                 if (row < MV) {
;                     const float* rp = (row < MPR) ? res_p + (size_t)row * DM : res_s + (size_t)(row - MPR) * DM;
;                     float s = 0.f;
; #pragma unroll
;                     for (int bj = 0; bj < 2; ++bj)
; #pragma unroll
;                         for (int n = 0; n < 2; ++n) { const int col = col0 + bj * 128 + n * 16; f32x4 r;
;                             if (RESB) { const u32x2 rw = *(const u32x2*)(resb + (size_t)row * DM + col); r = (f32x4){bf2f(rw.x & 0xffff), bf2f(rw.x >> 16), bf2f(rw.y & 0xffff), bf2f(rw.y >> 16)}; }
;                             else r = *(const f32x4*)(rp + col);
;                             const f32x4 v = r + acc[ai][bj][m][n] * scale;
;                             if (OUTF) *(f32x4*)(out + (size_t)row * DM + col) = v;
;                             else { u32x2 w; w.x = cvt_pk_bf16(v[0], v[1]); w.y = cvt_pk_bf16(v[2], v[3]); *(u32x2*)(outb + (size_t)row * DM + col) = w;
.LBB0_1294:
	s_cmp_lt_i32 s94, 2
	s_cbranch_scc0 .LBB0_1305
	v_lshl_add_u32 v190, s93, 8, v230
	v_lshl_or_b32 v191, s48, 8, v232
	v_lshlrev_b32_e32 v190, 11, v190
	v_lshl_add_u32 v190, v191, 1, v190
	v_lshlrev_b32_e32 v191, 1, v190
	global_load_dwordx2 v[134:135], v190, s[18:19]
	global_load_dwordx2 v[136:137], v190, s[18:19] offset:32
	global_load_dwordx2 v[138:139], v190, s[18:19] offset:256
	global_load_dwordx2 v[140:141], v190, s[18:19] offset:288
	v_add_u32_e32 v192, 0x8000, v190
	global_load_dwordx2 v[142:143], v192, s[18:19]
	global_load_dwordx2 v[144:145], v192, s[18:19] offset:32
	global_load_dwordx2 v[146:147], v192, s[18:19] offset:256
	global_load_dwordx2 v[148:149], v192, s[18:19] offset:288
	v_add_u32_e32 v192, 0x10000, v190
	global_load_dwordx2 v[150:151], v192, s[18:19]
	global_load_dwordx2 v[152:153], v192, s[18:19] offset:32
	global_load_dwordx2 v[154:155], v192, s[18:19] offset:256
	global_load_dwordx2 v[156:157], v192, s[18:19] offset:288
	v_add_u32_e32 v192, 0x18000, v190
	global_load_dwordx2 v[158:159], v192, s[18:19]
	global_load_dwordx2 v[160:161], v192, s[18:19] offset:32
	global_load_dwordx2 v[162:163], v192, s[18:19] offset:256
	global_load_dwordx2 v[164:165], v192, s[18:19] offset:288
	v_add_u32_e32 v192, 0x40000, v190
	global_load_dwordx2 v[166:167], v192, s[18:19]
	global_load_dwordx2 v[168:169], v192, s[18:19] offset:32
	global_load_dwordx2 v[170:171], v192, s[18:19] offset:256
	global_load_dwordx2 v[172:173], v192, s[18:19] offset:288
	v_add_u32_e32 v192, 0x48000, v190
	global_load_dwordx2 v[174:175], v192, s[18:19]
	global_load_dwordx2 v[176:177], v192, s[18:19] offset:32
	global_load_dwordx2 v[178:179], v192, s[18:19] offset:256
	global_load_dwordx2 v[180:181], v192, s[18:19] offset:288
	v_add_u32_e32 v192, 0x50000, v190
	global_load_dwordx2 v[182:183], v192, s[18:19]
	global_load_dwordx2 v[184:185], v192, s[18:19] offset:32
	global_load_dwordx2 v[186:187], v192, s[18:19] offset:256
	global_load_dwordx2 v[188:189], v192, s[18:19] offset:288
	s_waitcnt vmcnt(24)
	v_and_b32_e32 v194, 0xffff0000, v134
	v_lshlrev_b32_e32 v134, 16, v134
	v_and_b32_e32 v195, 0xffff0000, v135
	v_lshlrev_b32_e32 v135, 16, v135
	v_fma_f32 v90, v90, 0.5, v134
	v_fma_f32 v91, v91, 0.5, v194
	v_fma_f32 v92, v92, 0.5, v135
	v_fma_f32 v93, v93, 0.5, v195
	v_and_b32_e32 v194, 0xffff0000, v136
	v_lshlrev_b32_e32 v136, 16, v136
	v_and_b32_e32 v195, 0xffff0000, v137
	v_lshlrev_b32_e32 v137, 16, v137
	v_fma_f32 v82, v82, 0.5, v136
	v_fma_f32 v83, v83, 0.5, v194
	v_fma_f32 v84, v84, 0.5, v137
	v_fma_f32 v85, v85, 0.5, v195
	v_and_b32_e32 v194, 0xffff0000, v138
	v_lshlrev_b32_e32 v138, 16, v138
	v_and_b32_e32 v195, 0xffff0000, v139
	v_lshlrev_b32_e32 v139, 16, v139
	v_fma_f32 v70, v70, 0.5, v138
	v_fma_f32 v71, v71, 0.5, v194
	v_fma_f32 v72, v72, 0.5, v139
	v_fma_f32 v73, v73, 0.5, v195
	v_and_b32_e32 v194, 0xffff0000, v140
	v_lshlrev_b32_e32 v140, 16, v140
	v_and_b32_e32 v195, 0xffff0000, v141
	v_lshlrev_b32_e32 v141, 16, v141
	v_fma_f32 v58, v58, 0.5, v140
	v_fma_f32 v59, v59, 0.5, v194
	v_fma_f32 v60, v60, 0.5, v141
	v_fma_f32 v61, v61, 0.5, v195
	v_add_u32_e32 v192, 0x58000, v190
	global_load_dwordx2 v[134:135], v192, s[18:19]
	global_load_dwordx2 v[136:137], v192, s[18:19] offset:32
	global_load_dwordx2 v[138:139], v192, s[18:19] offset:256
	global_load_dwordx2 v[140:141], v192, s[18:19] offset:288
	global_store_dwordx4 v191, v[90:93], s[12:13]
	global_store_dwordx4 v191, v[82:85], s[12:13] offset:64
	global_store_dwordx4 v191, v[70:73], s[12:13] offset:512
	global_store_dwordx4 v191, v[58:61], s[12:13] offset:576
	s_waitcnt vmcnt(28)
	v_and_b32_e32 v194, 0xffff0000, v142
	v_lshlrev_b32_e32 v142, 16, v142
	v_and_b32_e32 v195, 0xffff0000, v143
	v_lshlrev_b32_e32 v143, 16, v143
	v_fma_f32 v66, v66, 0.5, v142
	v_fma_f32 v67, v67, 0.5, v194
	v_fma_f32 v68, v68, 0.5, v143
	v_fma_f32 v69, v69, 0.5, v195
	v_and_b32_e32 v194, 0xffff0000, v144
	v_lshlrev_b32_e32 v144, 16, v144
	v_and_b32_e32 v195, 0xffff0000, v145
	v_lshlrev_b32_e32 v145, 16, v145
	v_fma_f32 v54, v54, 0.5, v144
	v_fma_f32 v55, v55, 0.5, v194
	v_fma_f32 v56, v56, 0.5, v145
	v_fma_f32 v57, v57, 0.5, v195
	v_and_b32_e32 v194, 0xffff0000, v146
	v_lshlrev_b32_e32 v146, 16, v146
	v_and_b32_e32 v195, 0xffff0000, v147
	v_lshlrev_b32_e32 v147, 16, v147
	v_fma_f32 v46, v46, 0.5, v146
	v_fma_f32 v47, v47, 0.5, v194
	v_fma_f32 v48, v48, 0.5, v147
	v_fma_f32 v49, v49, 0.5, v195
	v_and_b32_e32 v194, 0xffff0000, v148
	v_lshlrev_b32_e32 v148, 16, v148
	v_and_b32_e32 v195, 0xffff0000, v149
	v_lshlrev_b32_e32 v149, 16, v149
	v_fma_f32 v38, v38, 0.5, v148
	v_fma_f32 v39, v39, 0.5, v194
	v_fma_f32 v40, v40, 0.5, v149
	v_fma_f32 v41, v41, 0.5, v195
	v_add_u32_e32 v193, 0x10000, v191
	global_store_dwordx4 v193, v[66:69], s[12:13]
	global_store_dwordx4 v193, v[54:57], s[12:13] offset:64
	global_store_dwordx4 v193, v[46:49], s[12:13] offset:512
	global_store_dwordx4 v193, v[38:41], s[12:13] offset:576
	s_waitcnt vmcnt(28)
	v_and_b32_e32 v194, 0xffff0000, v150
	v_lshlrev_b32_e32 v150, 16, v150
	v_and_b32_e32 v195, 0xffff0000, v151
	v_lshlrev_b32_e32 v151, 16, v151
	v_fma_f32 v42, v42, 0.5, v150
	v_fma_f32 v43, v43, 0.5, v194
	v_fma_f32 v44, v44, 0.5, v151
	v_fma_f32 v45, v45, 0.5, v195
	v_and_b32_e32 v194, 0xffff0000, v152
	v_lshlrev_b32_e32 v152, 16, v152
	v_and_b32_e32 v195, 0xffff0000, v153
	v_lshlrev_b32_e32 v153, 16, v153
	v_fma_f32 v30, v30, 0.5, v152
	v_fma_f32 v31, v31, 0.5, v194
	v_fma_f32 v32, v32, 0.5, v153
	v_fma_f32 v33, v33, 0.5, v195
	v_and_b32_e32 v194, 0xffff0000, v154
	v_lshlrev_b32_e32 v154, 16, v154
	v_and_b32_e32 v195, 0xffff0000, v155
	v_lshlrev_b32_e32 v155, 16, v155
	v_fma_f32 v26, v26, 0.5, v154
	v_fma_f32 v27, v27, 0.5, v194
	v_fma_f32 v28, v28, 0.5, v155
	v_fma_f32 v29, v29, 0.5, v195
	v_and_b32_e32 v194, 0xffff0000, v156
	v_lshlrev_b32_e32 v156, 16, v156
	v_and_b32_e32 v195, 0xffff0000, v157
	v_lshlrev_b32_e32 v157, 16, v157
	v_fma_f32 v18, v18, 0.5, v156
	v_fma_f32 v19, v19, 0.5, v194
	v_fma_f32 v20, v20, 0.5, v157
	v_fma_f32 v21, v21, 0.5, v195
	v_add_u32_e32 v193, 0x20000, v191
	global_store_dwordx4 v193, v[42:45], s[12:13]
	global_store_dwordx4 v193, v[30:33], s[12:13] offset:64
	global_store_dwordx4 v193, v[26:29], s[12:13] offset:512
	global_store_dwordx4 v193, v[18:21], s[12:13] offset:576
	s_waitcnt vmcnt(28)
; __device__ __forceinline__ unsigned cvt_pk_bf16(float lo, float hi) { unsigned r; asm volatile("v_cvt_pk_bf16_f32 %0, %1, %2" : "=v"(r) : "v"(lo), "v"(hi)); return r; }
;     __device__ __forceinline__ void operator()(const f32x4 (&acc)[2][2][4][2], const pg8::Unit& u, int wr, int wc, int fr, int fq) const {
;     ...
;                     for (int bj = 0; bj < 2; ++bj)
; #pragma unroll
;                         for (int n = 0; n < 2; ++n) { const int col = col0 + bj * 128 + n * 16; f32x4 r;
;                             if (RESB) { const u32x2 rw = *(const u32x2*)(resb + (size_t)row * DM + col); r = (f32x4){bf2f(rw.x & 0xffff), bf2f(rw.x >> 16), bf2f(rw.y & 0xffff), bf2f(rw.y >> 16)}; }
;                             else r = *(const f32x4*)(rp + col);
;                             const f32x4 v = r + acc[ai][bj][m][n] * scale;
;                             if (OUTF) *(f32x4*)(out + (size_t)row * DM + col) = v;
;                             else { u32x2 w; w.x = cvt_pk_bf16(v[0], v[1]); w.y = cvt_pk_bf16(v[2], v[3]); *(u32x2*)(outb + (size_t)row * DM + col) = w;
	v_and_b32_e32 v194, 0xffff0000, v158
	v_lshlrev_b32_e32 v158, 16, v158
	v_and_b32_e32 v195, 0xffff0000, v159
	v_lshlrev_b32_e32 v159, 16, v159
	v_fma_f32 v22, v22, 0.5, v158
	v_fma_f32 v23, v23, 0.5, v194
	v_fma_f32 v24, v24, 0.5, v159
	v_fma_f32 v25, v25, 0.5, v195
	v_and_b32_e32 v194, 0xffff0000, v160
	v_lshlrev_b32_e32 v160, 16, v160
	v_and_b32_e32 v195, 0xffff0000, v161
	v_lshlrev_b32_e32 v161, 16, v161
	v_fma_f32 v14, v14, 0.5, v160
	v_fma_f32 v15, v15, 0.5, v194
	v_fma_f32 v16, v16, 0.5, v161
	v_fma_f32 v17, v17, 0.5, v195
	v_and_b32_e32 v194, 0xffff0000, v162
	v_lshlrev_b32_e32 v162, 16, v162
	v_and_b32_e32 v195, 0xffff0000, v163
	v_lshlrev_b32_e32 v163, 16, v163
	v_fma_f32 v10, v10, 0.5, v162
	v_fma_f32 v11, v11, 0.5, v194
	v_fma_f32 v12, v12, 0.5, v163
	v_fma_f32 v13, v13, 0.5, v195
	v_and_b32_e32 v194, 0xffff0000, v164
	v_lshlrev_b32_e32 v164, 16, v164
	v_and_b32_e32 v195, 0xffff0000, v165
	v_lshlrev_b32_e32 v165, 16, v165
	v_fma_f32 v6, v6, 0.5, v164
	v_fma_f32 v7, v7, 0.5, v194
	v_fma_f32 v8, v8, 0.5, v165
	v_fma_f32 v9, v9, 0.5, v195
	v_add_u32_e32 v193, 0x30000, v191
	global_store_dwordx4 v193, v[22:25], s[12:13]
	global_store_dwordx4 v193, v[14:17], s[12:13] offset:64
	global_store_dwordx4 v193, v[10:13], s[12:13] offset:512
	global_store_dwordx4 v193, v[6:9], s[12:13] offset:576
	s_waitcnt vmcnt(28)
	v_and_b32_e32 v194, 0xffff0000, v166
	v_lshlrev_b32_e32 v166, 16, v166
	v_and_b32_e32 v195, 0xffff0000, v167
	v_lshlrev_b32_e32 v167, 16, v167
	v_fma_f32 v130, v130, 0.5, v166
	v_fma_f32 v131, v131, 0.5, v194
	v_fma_f32 v132, v132, 0.5, v167
	v_fma_f32 v133, v133, 0.5, v195
	v_and_b32_e32 v194, 0xffff0000, v168
	v_lshlrev_b32_e32 v168, 16, v168
	v_and_b32_e32 v195, 0xffff0000, v169
	v_lshlrev_b32_e32 v169, 16, v169
	v_fma_f32 v126, v126, 0.5, v168
	v_fma_f32 v127, v127, 0.5, v194
	v_fma_f32 v128, v128, 0.5, v169
	v_fma_f32 v129, v129, 0.5, v195
	v_and_b32_e32 v194, 0xffff0000, v170
	v_lshlrev_b32_e32 v170, 16, v170
	v_and_b32_e32 v195, 0xffff0000, v171
	v_lshlrev_b32_e32 v171, 16, v171
	v_fma_f32 v122, v122, 0.5, v170
	v_fma_f32 v123, v123, 0.5, v194
	v_fma_f32 v124, v124, 0.5, v171
	v_fma_f32 v125, v125, 0.5, v195
	v_and_b32_e32 v194, 0xffff0000, v172
	v_lshlrev_b32_e32 v172, 16, v172
	v_and_b32_e32 v195, 0xffff0000, v173
	v_lshlrev_b32_e32 v173, 16, v173
	v_fma_f32 v118, v118, 0.5, v172
	v_fma_f32 v119, v119, 0.5, v194
	v_fma_f32 v120, v120, 0.5, v173
	v_fma_f32 v121, v121, 0.5, v195
	v_add_u32_e32 v193, 0x80000, v191
	global_store_dwordx4 v193, v[130:133], s[12:13]
	global_store_dwordx4 v193, v[126:129], s[12:13] offset:64
	global_store_dwordx4 v193, v[122:125], s[12:13] offset:512
	global_store_dwordx4 v193, v[118:121], s[12:13] offset:576
	s_waitcnt vmcnt(28)
	v_and_b32_e32 v194, 0xffff0000, v174
	v_lshlrev_b32_e32 v174, 16, v174
	v_and_b32_e32 v195, 0xffff0000, v175
	v_lshlrev_b32_e32 v175, 16, v175
	v_fma_f32 v114, v114, 0.5, v174
	v_fma_f32 v115, v115, 0.5, v194
	v_fma_f32 v116, v116, 0.5, v175
	v_fma_f32 v117, v117, 0.5, v195
	v_and_b32_e32 v194, 0xffff0000, v176
	v_lshlrev_b32_e32 v176, 16, v176
	v_and_b32_e32 v195, 0xffff0000, v177
	v_lshlrev_b32_e32 v177, 16, v177
	v_fma_f32 v110, v110, 0.5, v176
	v_fma_f32 v111, v111, 0.5, v194
	v_fma_f32 v112, v112, 0.5, v177
	v_fma_f32 v113, v113, 0.5, v195
	v_and_b32_e32 v194, 0xffff0000, v178
	v_lshlrev_b32_e32 v178, 16, v178
	v_and_b32_e32 v195, 0xffff0000, v179
	v_lshlrev_b32_e32 v179, 16, v179
	v_fma_f32 v106, v106, 0.5, v178
	v_fma_f32 v107, v107, 0.5, v194
	v_fma_f32 v108, v108, 0.5, v179
	v_fma_f32 v109, v109, 0.5, v195
	v_and_b32_e32 v194, 0xffff0000, v180
	v_lshlrev_b32_e32 v180, 16, v180
	v_and_b32_e32 v195, 0xffff0000, v181
	v_lshlrev_b32_e32 v181, 16, v181
	v_fma_f32 v102, v102, 0.5, v180
	v_fma_f32 v103, v103, 0.5, v194
	v_fma_f32 v104, v104, 0.5, v181
	v_fma_f32 v105, v105, 0.5, v195
	v_add_u32_e32 v193, 0x90000, v191
	global_store_dwordx4 v193, v[114:117], s[12:13]
	global_store_dwordx4 v193, v[110:113], s[12:13] offset:64
	global_store_dwordx4 v193, v[106:109], s[12:13] offset:512
	global_store_dwordx4 v193, v[102:105], s[12:13] offset:576
	s_waitcnt vmcnt(28)
	v_and_b32_e32 v194, 0xffff0000, v182
	v_lshlrev_b32_e32 v182, 16, v182
	v_and_b32_e32 v195, 0xffff0000, v183
	v_lshlrev_b32_e32 v183, 16, v183
	v_fma_f32 v98, v98, 0.5, v182
	v_fma_f32 v99, v99, 0.5, v194
	v_fma_f32 v100, v100, 0.5, v183
	v_fma_f32 v101, v101, 0.5, v195
	v_and_b32_e32 v194, 0xffff0000, v184
	v_lshlrev_b32_e32 v184, 16, v184
	v_and_b32_e32 v195, 0xffff0000, v185
	v_lshlrev_b32_e32 v185, 16, v185
	v_fma_f32 v94, v94, 0.5, v184
	v_fma_f32 v95, v95, 0.5, v194
	v_fma_f32 v96, v96, 0.5, v185
	v_fma_f32 v97, v97, 0.5, v195
	v_and_b32_e32 v194, 0xffff0000, v186
	v_lshlrev_b32_e32 v186, 16, v186
	v_and_b32_e32 v195, 0xffff0000, v187
	v_lshlrev_b32_e32 v187, 16, v187
	v_fma_f32 v86, v86, 0.5, v186
	v_fma_f32 v87, v87, 0.5, v194
	v_fma_f32 v88, v88, 0.5, v187
	v_fma_f32 v89, v89, 0.5, v195
	v_and_b32_e32 v194, 0xffff0000, v188
	v_lshlrev_b32_e32 v188, 16, v188
	v_and_b32_e32 v195, 0xffff0000, v189
	v_lshlrev_b32_e32 v189, 16, v189
	v_fma_f32 v78, v78, 0.5, v188
	v_fma_f32 v79, v79, 0.5, v194
	v_fma_f32 v80, v80, 0.5, v189
	v_fma_f32 v81, v81, 0.5, v195
	v_add_u32_e32 v193, 0xa0000, v191
	global_store_dwordx4 v193, v[98:101], s[12:13]
	global_store_dwordx4 v193, v[94:97], s[12:13] offset:64
	global_store_dwordx4 v193, v[86:89], s[12:13] offset:512
	global_store_dwordx4 v193, v[78:81], s[12:13] offset:576
	s_waitcnt vmcnt(28)
	v_and_b32_e32 v194, 0xffff0000, v134
	v_lshlrev_b32_e32 v134, 16, v134
	v_and_b32_e32 v195, 0xffff0000, v135
	v_lshlrev_b32_e32 v135, 16, v135
	v_fma_f32 v74, v74, 0.5, v134
	v_fma_f32 v75, v75, 0.5, v194
	v_fma_f32 v76, v76, 0.5, v135
	v_fma_f32 v77, v77, 0.5, v195
	v_and_b32_e32 v194, 0xffff0000, v136
	v_lshlrev_b32_e32 v136, 16, v136
	v_and_b32_e32 v195, 0xffff0000, v137
	v_lshlrev_b32_e32 v137, 16, v137
	v_fma_f32 v62, v62, 0.5, v136
	v_fma_f32 v63, v63, 0.5, v194
	v_fma_f32 v64, v64, 0.5, v137
	v_fma_f32 v65, v65, 0.5, v195
	v_and_b32_e32 v194, 0xffff0000, v138
	v_lshlrev_b32_e32 v138, 16, v138
	v_and_b32_e32 v195, 0xffff0000, v139
	v_lshlrev_b32_e32 v139, 16, v139
	v_fma_f32 v50, v50, 0.5, v138
	v_fma_f32 v51, v51, 0.5, v194
	v_fma_f32 v52, v52, 0.5, v139
	v_fma_f32 v53, v53, 0.5, v195
	v_and_b32_e32 v194, 0xffff0000, v140
	v_lshlrev_b32_e32 v140, 16, v140
	v_and_b32_e32 v195, 0xffff0000, v141
	v_lshlrev_b32_e32 v141, 16, v141
	v_fma_f32 v34, v34, 0.5, v140
	v_fma_f32 v35, v35, 0.5, v194
	v_fma_f32 v36, v36, 0.5, v141
	v_fma_f32 v37, v37, 0.5, v195
	v_add_u32_e32 v193, 0xb0000, v191
	global_store_dwordx4 v193, v[74:77], s[12:13]
	global_store_dwordx4 v193, v[62:65], s[12:13] offset:64
	global_store_dwordx4 v193, v[50:53], s[12:13] offset:512
	global_store_dwordx4 v193, v[34:37], s[12:13] offset:576
	s_branch .Lp9e_done

; #define PG8_LAS __attribute__((address_space(3)))
; #define PG8_BAR __builtin_amdgcn_s_barrier()
; template <class Epi, class Sched, bool ALIGN_EPI = false, bool SP2 = false, class Bg = BgNone>
; __device__ __forceinline__ void gemm_phase(PG8_LAS unsigned char* lds, const Gemm g, const Sched& S, const Epi& E, const int wave_sg, const Bg& bg = Bg()) {
;     ...
;         if (cur.split > 1) {
;             float* ab = S.acc_buf + (size_t)cur.pn * (64 * 512) + tid;
; #pragma unroll
;             for (int m = 0; m < 4; ++m)
; #pragma unroll
;                 for (int bj = 0; bj < 2; ++bj)
; #pragma unroll
;                     for (int n = 0; n < 2; ++n)
; #pragma unroll
;                         for (int c = 0; c < 4; ++c) unsafeAtomicAdd(ab + (((m * 2 + bj) * 2 + n) * 4 + c) * 512, acc[0][bj][m][n][c]);
;             __threadfence();
;             PG8_LAS unsigned* flag = (PG8_LAS unsigned*)(lds + STAGE_BYTES);
;             PG8_BAR;
;             if (tid == 0) { const unsigned old = __hip_atomic_fetch_add(S.cnt + cur.pn, 1u, __ATOMIC_ACQ_REL, __HIP_MEMORY_SCOPE_AGENT); *flag = (old == (unsigned)cur.split - 1u) ? 1u : 0u; }
.LBB0_1308:
	s_and_b64 vcc, exec, s[6:7]
	s_cbranch_vccz .LBB0_1342
	s_branch .LBB0_1344
.LBB0_1316:
	s_ashr_i32 s49, s48, 31
	s_lshl_b64 s[52:53], s[48:49], 17
	v_lshl_add_u64 v[34:35], v[204:205], 0, s[52:53]
	v_add_co_u32_e32 v36, vcc, 0x1000, v34
	global_atomic_add_f32 v[34:35], v90, off
	global_atomic_add_f32 v[34:35], v91, off offset:2048
	v_addc_co_u32_e32 v37, vcc, 0, v35, vcc
	global_atomic_add_f32 v[36:37], v92, off
	global_atomic_add_f32 v[36:37], v93, off offset:2048
	v_add_co_u32_e32 v36, vcc, 0x2000, v34
	s_mov_b32 s45, 0x10000
	s_nop 0
	v_addc_co_u32_e32 v37, vcc, 0, v35, vcc
	global_atomic_add_f32 v[36:37], v82, off
	global_atomic_add_f32 v[36:37], v83, off offset:2048
	v_add_co_u32_e32 v36, vcc, 0x3000, v34
	s_nop 1
	v_addc_co_u32_e32 v37, vcc, 0, v35, vcc
	global_atomic_add_f32 v[36:37], v84, off
	global_atomic_add_f32 v[36:37], v85, off offset:2048
	v_add_co_u32_e32 v36, vcc, 0x4000, v34
	s_nop 1
	v_addc_co_u32_e32 v37, vcc, 0, v35, vcc
	global_atomic_add_f32 v[36:37], v70, off
	global_atomic_add_f32 v[36:37], v71, off offset:2048
	v_add_co_u32_e32 v36, vcc, 0x5000, v34
	s_nop 1
	v_addc_co_u32_e32 v37, vcc, 0, v35, vcc
	global_atomic_add_f32 v[36:37], v72, off
	global_atomic_add_f32 v[36:37], v73, off offset:2048
	v_add_co_u32_e32 v36, vcc, 0x6000, v34
	s_nop 1
	v_addc_co_u32_e32 v37, vcc, 0, v35, vcc
	global_atomic_add_f32 v[36:37], v58, off
	global_atomic_add_f32 v[36:37], v59, off offset:2048
	v_add_co_u32_e32 v36, vcc, 0x7000, v34
	s_nop 1
	v_addc_co_u32_e32 v37, vcc, 0, v35, vcc
	global_atomic_add_f32 v[36:37], v60, off
	global_atomic_add_f32 v[36:37], v61, off offset:2048
	v_add_co_u32_e32 v36, vcc, 0x8000, v34
	s_nop 1
	v_addc_co_u32_e32 v37, vcc, 0, v35, vcc
	global_atomic_add_f32 v[36:37], v66, off
	global_atomic_add_f32 v[36:37], v67, off offset:2048
	v_add_co_u32_e32 v36, vcc, 0x9000, v34
	s_nop 1
	v_addc_co_u32_e32 v37, vcc, 0, v35, vcc
	global_atomic_add_f32 v[36:37], v68, off
	global_atomic_add_f32 v[36:37], v69, off offset:2048
	v_add_co_u32_e32 v36, vcc, 0xa000, v34
	s_nop 1
	v_addc_co_u32_e32 v37, vcc, 0, v35, vcc
	global_atomic_add_f32 v[36:37], v54, off
	global_atomic_add_f32 v[36:37], v55, off offset:2048
	v_add_co_u32_e32 v36, vcc, 0xb000, v34
	s_nop 1
	v_addc_co_u32_e32 v37, vcc, 0, v35, vcc
	global_atomic_add_f32 v[36:37], v56, off
	global_atomic_add_f32 v[36:37], v57, off offset:2048
	v_add_co_u32_e32 v36, vcc, 0xc000, v34
	s_nop 1
	v_addc_co_u32_e32 v37, vcc, 0, v35, vcc
	global_atomic_add_f32 v[36:37], v46, off
	global_atomic_add_f32 v[36:37], v47, off offset:2048
	v_add_co_u32_e32 v36, vcc, 0xd000, v34
	s_nop 1
	v_addc_co_u32_e32 v37, vcc, 0, v35, vcc
	global_atomic_add_f32 v[36:37], v48, off
	global_atomic_add_f32 v[36:37], v49, off offset:2048
	v_add_co_u32_e32 v36, vcc, 0xe000, v34
	s_nop 1
	v_addc_co_u32_e32 v37, vcc, 0, v35, vcc
	global_atomic_add_f32 v[36:37], v38, off
	global_atomic_add_f32 v[36:37], v39, off offset:2048
	v_add_co_u32_e32 v36, vcc, 0xf000, v34
	s_nop 1
	v_addc_co_u32_e32 v37, vcc, 0, v35, vcc
	global_atomic_add_f32 v[36:37], v40, off
	global_atomic_add_f32 v[36:37], v41, off offset:2048
	v_add_co_u32_e32 v36, vcc, s45, v34
	s_mov_b32 s45, 0x12000
	s_nop 0
	v_addc_co_u32_e32 v37, vcc, 0, v35, vcc
	global_atomic_add_f32 v[36:37], v42, off
	global_atomic_add_f32 v[36:37], v43, off offset:2048
	v_add_co_u32_e32 v36, vcc, 0x11000, v34
	s_nop 1
	v_addc_co_u32_e32 v37, vcc, 0, v35, vcc
	global_atomic_add_f32 v[36:37], v44, off
	global_atomic_add_f32 v[36:37], v45, off offset:2048
	v_add_co_u32_e32 v36, vcc, s45, v34
	s_mov_b32 s45, 0x14000
	s_nop 0
	v_addc_co_u32_e32 v37, vcc, 0, v35, vcc
	global_atomic_add_f32 v[36:37], v30, off
	global_atomic_add_f32 v[36:37], v31, off offset:2048
	v_add_co_u32_e32 v30, vcc, 0x13000, v34
	s_nop 1
	v_addc_co_u32_e32 v31, vcc, 0, v35, vcc
	global_atomic_add_f32 v[30:31], v32, off
	global_atomic_add_f32 v[30:31], v33, off offset:2048
	v_add_co_u32_e32 v30, vcc, s45, v34
	s_mov_b32 s45, 0x16000
	s_nop 0
	v_addc_co_u32_e32 v31, vcc, 0, v35, vcc
	global_atomic_add_f32 v[30:31], v26, off
	global_atomic_add_f32 v[30:31], v27, off offset:2048
	v_add_co_u32_e32 v26, vcc, 0x15000, v34
	s_nop 1
	v_addc_co_u32_e32 v27, vcc, 0, v35, vcc
	global_atomic_add_f32 v[26:27], v28, off
	global_atomic_add_f32 v[26:27], v29, off offset:2048
	v_add_co_u32_e32 v26, vcc, s45, v34
	s_mov_b32 s45, 0x18000
	s_nop 0
	v_addc_co_u32_e32 v27, vcc, 0, v35, vcc
	global_atomic_add_f32 v[26:27], v18, off
	global_atomic_add_f32 v[26:27], v19, off offset:2048
	v_add_co_u32_e32 v18, vcc, 0x17000, v34
	s_nop 1
	v_addc_co_u32_e32 v19, vcc, 0, v35, vcc
	global_atomic_add_f32 v[18:19], v20, off
	global_atomic_add_f32 v[18:19], v21, off offset:2048
	v_add_co_u32_e32 v18, vcc, s45, v34
	s_mov_b32 s45, 0x1a000
	s_nop 0
	v_addc_co_u32_e32 v19, vcc, 0, v35, vcc
	global_atomic_add_f32 v[18:19], v22, off
	global_atomic_add_f32 v[18:19], v23, off offset:2048
	v_add_co_u32_e32 v18, vcc, 0x19000, v34
	s_nop 1
	v_addc_co_u32_e32 v19, vcc, 0, v35, vcc
	global_atomic_add_f32 v[18:19], v24, off
	global_atomic_add_f32 v[18:19], v25, off offset:2048
	v_add_co_u32_e32 v18, vcc, s45, v34
	s_mov_b32 s45, 0x1c000
	s_nop 0
	v_addc_co_u32_e32 v19, vcc, 0, v35, vcc
	global_atomic_add_f32 v[18:19], v14, off
	global_atomic_add_f32 v[18:19], v15, off offset:2048
	v_add_co_u32_e32 v14, vcc, 0x1b000, v34
	s_nop 1
	v_addc_co_u32_e32 v15, vcc, 0, v35, vcc
	global_atomic_add_f32 v[14:15], v16, off
	global_atomic_add_f32 v[14:15], v17, off offset:2048
	v_add_co_u32_e32 v14, vcc, s45, v34
	s_nop 1
	v_addc_co_u32_e32 v15, vcc, 0, v35, vcc
	global_atomic_add_f32 v[14:15], v10, off
	global_atomic_add_f32 v[14:15], v11, off offset:2048
	v_add_co_u32_e32 v10, vcc, 0x1d000, v34
	s_nop 1
	v_addc_co_u32_e32 v11, vcc, 0, v35, vcc
	global_atomic_add_f32 v[10:11], v12, off
	global_atomic_add_f32 v[10:11], v13, off offset:2048
	v_add_co_u32_e32 v10, vcc, 0x1e000, v34
	s_nop 1
	v_addc_co_u32_e32 v11, vcc, 0, v35, vcc
	global_atomic_add_f32 v[10:11], v6, off
	global_atomic_add_f32 v[10:11], v7, off offset:2048
	v_add_co_u32_e32 v6, vcc, 0x1f000, v34
	s_nop 1
	v_addc_co_u32_e32 v7, vcc, 0, v35, vcc
	global_atomic_add_f32 v[6:7], v8, off
	global_atomic_add_f32 v[6:7], v9, off offset:2048
	buffer_wbl2 sc1
	s_waitcnt vmcnt(0)
	buffer_inv sc1
	s_barrier
	s_and_saveexec_b64 s[52:53], s[0:1]
	s_cbranch_execz .LBB0_1320
	s_mov_b64 s[56:57], exec
	v_mbcnt_lo_u32_b32 v0, s56, 0
	v_mbcnt_hi_u32_b32 v0, s57, v0
	v_cmp_eq_u32_e32 vcc, 0, v0
	s_and_saveexec_b64 s[54:55], vcc
	s_cbranch_execz .LBB0_1319
	s_lshl_b64 s[58:59], s[48:49], 2
	s_add_u32 s58, s76, s58
	s_addc_u32 s59, s77, s59
	s_bcnt1_i32_b64 s45, s[56:57]
	v_mov_b32_e32 v6, s45
	buffer_wbl2 sc1
	global_atomic_add v6, v1, v6, s[58:59] sc0
	s_waitcnt vmcnt(0)
	buffer_inv sc1

; template <class Epi, class Sched, bool ALIGN_EPI = false, bool SP2 = false, class Bg = BgNone>
; __device__ __forceinline__ void gemm_phase(PG8_LAS unsigned char* lds, const Gemm g, const Sched& S, const Epi& E, const int wave_sg, const Bg& bg = Bg()) {
;     ...
;         } else
;         if constexpr (!Epi::AFTER_DRAIN) { E(acc, cur, wr, wc, fr, fq); S.done(cur); }
;         if (!has_next) break;
.Lp9e_done:
	s_and_b64 vcc, exec, s[6:7]
	s_mov_b64 s[6:7], -1
	s_cbranch_vccnz .LBB0_1308
